# grid-barrier poll: 16 counter loads issued together, one wait (was 7 serial round trips per poll)
# baseline (speedup 1.0000x reference)
; __device__ __forceinline__ unsigned xb_ld(unsigned* p)              { return __hip_atomic_load(p, __ATOMIC_RELAXED, __HIP_MEMORY_SCOPE_AGENT); }
; __device__ __forceinline__ void xcd_barrier_complete(unsigned* bar, unsigned x, unsigned& nloc, unsigned& nx) {
;     ...
;     for (;;) {
;         sum = 0u; cnt = 0u; mine = 0u;
; #pragma unroll
;         for (unsigned j = 0; j < 16; ++j) { const unsigned c = xb_ld(&bar[XB_XCNT(j)]); sum += c; cnt += (c > 0u) ? 1u : 0u; mine = (j == x) ? c : mine; }
;         if (sum == G) break;
;         __builtin_amdgcn_s_sleep(1);
;         if ((++sp & 255u) == 0u) { if (xb_ld(&bar[XB_TMO])) break; if (sp > XB_SPIN_CAP) { atomicAdd(&bar[XB_TMO], 1u); break; } }
;     }
.LBB0_571:
	v_mov_b32_e32 v18, 0
	s_waitcnt lgkmcnt(0)
	global_load_dword v0, v18, s[4:5] sc1
	global_load_dword v2, v18, s[6:7] sc1
	global_load_dword v3, v18, s[8:9] sc1
	global_load_dword v4, v18, s[10:11] sc1
	global_load_dword v5, v18, s[12:13] sc1
	global_load_dword v6, v18, s[14:15] sc1
	global_load_dword v7, v18, s[16:17] sc1
	global_load_dword v8, v18, s[18:19] sc1
	global_load_dword v9, v18, s[20:21] sc1
	global_load_dword v10, v18, s[22:23] sc1
	global_load_dword v11, v18, s[24:25] sc1
	global_load_dword v12, v18, s[26:27] sc1
	global_load_dword v13, v18, s[28:29] sc1
	global_load_dword v14, v18, s[30:31] sc1
	global_load_dword v15, v18, s[34:35] sc1
	global_load_dword v16, v18, s[36:37] sc1
	v_readlane_b32 s46, v254, 8
	s_or_b64 s[44:45], s[44:45], exec
	s_or_b64 s[42:43], s[42:43], exec
	s_waitcnt vmcnt(0) lgkmcnt(0)
	v_add_u32_e32 v6, v2, v0
	v_add_u32_e32 v6, v6, v3
	v_add_u32_e32 v8, v6, v4
	v_add_u32_e32 v8, v8, v5
	v_add_u32_e32 v10, v8, v6
	v_add_u32_e32 v10, v10, v7
	v_add_u32_e32 v12, v10, v8
	v_add_u32_e32 v12, v12, v9
	v_add_u32_e32 v14, v12, v10
	v_add_u32_e32 v14, v14, v11
	v_add_u32_e32 v16, v14, v12
	v_add_u32_e32 v16, v16, v13
	v_add_u32_e32 v18, v16, v14
	v_add_u32_e32 v18, v18, v15
	v_add_u32_e32 v17, v18, v16
	v_cmp_ne_u32_e32 vcc, s46, v17
	s_and_saveexec_b64 s[46:47], vcc
	s_cbranch_execz .LBB0_570
	s_and_b32 s50, s60, 0xff
	s_mov_b64 s[48:49], -1
	s_cmp_eq_u32 s50, 0
	s_mov_b64 s[52:53], -1
	s_mov_b64 s[50:51], -1
	s_sleep 1
	s_cbranch_scc1 .LBB0_574
	s_and_saveexec_b64 s[68:69], s[52:53]
	s_cbranch_execz .LBB0_569
	s_branch .LBB0_577

; __device__ __forceinline__ unsigned xb_ld(unsigned* p)              { return __hip_atomic_load(p, __ATOMIC_RELAXED, __HIP_MEMORY_SCOPE_AGENT); }
; __device__ __forceinline__ void xcd_barrier_complete(unsigned* bar, unsigned x, unsigned& nloc, unsigned& nx) {
;     ...
;     for (;;) {
;         sum = 0u; cnt = 0u; mine = 0u;
; #pragma unroll
;         for (unsigned j = 0; j < 16; ++j) { const unsigned c = xb_ld(&bar[XB_XCNT(j)]); sum += c; cnt += (c > 0u) ? 1u : 0u; mine = (j == x) ? c : mine; }
;         if (sum == G) break;
;         __builtin_amdgcn_s_sleep(1);
;         if ((++sp & 255u) == 0u) { if (xb_ld(&bar[XB_TMO])) break; if (sp > XB_SPIN_CAP) { atomicAdd(&bar[XB_TMO], 1u); break; } }
;     }
.LBB0_814:
	v_mov_b32_e32 v18, 0
	s_waitcnt lgkmcnt(0)
	global_load_dword v0, v18, s[4:5] sc1
	global_load_dword v2, v18, s[6:7] sc1
	global_load_dword v3, v18, s[8:9] sc1
	global_load_dword v4, v18, s[10:11] sc1
	global_load_dword v5, v18, s[12:13] sc1
	global_load_dword v6, v18, s[14:15] sc1
	global_load_dword v7, v18, s[16:17] sc1
	global_load_dword v8, v18, s[18:19] sc1
	global_load_dword v9, v18, s[20:21] sc1
	global_load_dword v10, v18, s[22:23] sc1
	global_load_dword v11, v18, s[24:25] sc1
	global_load_dword v12, v18, s[26:27] sc1
	global_load_dword v13, v18, s[28:29] sc1
	global_load_dword v14, v18, s[30:31] sc1
	global_load_dword v15, v18, s[34:35] sc1
	global_load_dword v16, v18, s[36:37] sc1
	v_readlane_b32 s46, v254, 8
	s_or_b64 s[44:45], s[44:45], exec
	s_or_b64 s[42:43], s[42:43], exec
	s_waitcnt vmcnt(0) lgkmcnt(0)
	v_add_u32_e32 v6, v2, v0
	v_add_u32_e32 v6, v6, v3
	v_add_u32_e32 v8, v6, v4
	v_add_u32_e32 v8, v8, v5
	v_add_u32_e32 v10, v8, v6
	v_add_u32_e32 v10, v10, v7
	v_add_u32_e32 v12, v10, v8
	v_add_u32_e32 v12, v12, v9
	v_add_u32_e32 v14, v12, v10
	v_add_u32_e32 v14, v14, v11
	v_add_u32_e32 v16, v14, v12
	v_add_u32_e32 v16, v16, v13
	v_add_u32_e32 v18, v16, v14
	v_add_u32_e32 v18, v18, v15
	v_add_u32_e32 v17, v18, v16
	v_cmp_ne_u32_e32 vcc, s46, v17
	s_and_saveexec_b64 s[46:47], vcc
	s_cbranch_execz .LBB0_813
	s_and_b32 s50, s61, 0xff
	s_mov_b64 s[48:49], -1
	s_cmp_eq_u32 s50, 0
	s_mov_b64 s[52:53], -1
	s_mov_b64 s[50:51], -1
	s_sleep 1
	s_cbranch_scc1 .LBB0_817
	s_and_saveexec_b64 s[68:69], s[52:53]
	s_cbranch_execz .LBB0_812
	s_branch .LBB0_820

; __device__ __forceinline__ unsigned xb_ld(unsigned* p)              { return __hip_atomic_load(p, __ATOMIC_RELAXED, __HIP_MEMORY_SCOPE_AGENT); }
; __device__ __forceinline__ void xcd_barrier_complete(unsigned* bar, unsigned x, unsigned& nloc, unsigned& nx) {
;     ...
;     for (;;) {
;         sum = 0u; cnt = 0u; mine = 0u;
; #pragma unroll
;         for (unsigned j = 0; j < 16; ++j) { const unsigned c = xb_ld(&bar[XB_XCNT(j)]); sum += c; cnt += (c > 0u) ? 1u : 0u; mine = (j == x) ? c : mine; }
;         if (sum == G) break;
;         __builtin_amdgcn_s_sleep(1);
;         if ((++sp & 255u) == 0u) { if (xb_ld(&bar[XB_TMO])) break; if (sp > XB_SPIN_CAP) { atomicAdd(&bar[XB_TMO], 1u); break; } }
;     }
.LBB0_888:
	v_mov_b32_e32 v18, 0
	s_waitcnt lgkmcnt(0)
	global_load_dword v0, v18, s[4:5] sc1
	global_load_dword v2, v18, s[6:7] sc1
	global_load_dword v3, v18, s[8:9] sc1
	global_load_dword v4, v18, s[10:11] sc1
	global_load_dword v5, v18, s[12:13] sc1
	global_load_dword v6, v18, s[14:15] sc1
	global_load_dword v7, v18, s[16:17] sc1
	global_load_dword v8, v18, s[18:19] sc1
	global_load_dword v9, v18, s[20:21] sc1
	global_load_dword v10, v18, s[22:23] sc1
	global_load_dword v11, v18, s[24:25] sc1
	global_load_dword v12, v18, s[26:27] sc1
	global_load_dword v13, v18, s[28:29] sc1
	global_load_dword v14, v18, s[30:31] sc1
	global_load_dword v15, v18, s[38:39] sc1
	global_load_dword v16, v18, s[40:41] sc1
	v_readlane_b32 s50, v254, 8
	s_or_b64 s[48:49], s[48:49], exec
	s_or_b64 s[46:47], s[46:47], exec
	s_waitcnt vmcnt(0) lgkmcnt(0)
	v_add_u32_e32 v6, v2, v0
	v_add_u32_e32 v6, v6, v3
	v_add_u32_e32 v8, v6, v4
	v_add_u32_e32 v8, v8, v5
	v_add_u32_e32 v10, v8, v6
	v_add_u32_e32 v10, v10, v7
	v_add_u32_e32 v12, v10, v8
	v_add_u32_e32 v12, v12, v9
	v_add_u32_e32 v14, v12, v10
	v_add_u32_e32 v14, v14, v11
	v_add_u32_e32 v16, v14, v12
	v_add_u32_e32 v16, v16, v13
	v_add_u32_e32 v18, v16, v14
	v_add_u32_e32 v18, v18, v15
	v_add_u32_e32 v17, v18, v16
	v_cmp_ne_u32_e32 vcc, s50, v17
	s_and_saveexec_b64 s[50:51], vcc
	s_cbranch_execz .LBB0_887
	s_and_b32 s62, s61, 0xff
	s_mov_b64 s[52:53], -1
	s_cmp_eq_u32 s62, 0
	s_mov_b64 s[70:71], -1
	s_mov_b64 s[68:69], -1
	s_sleep 1
	s_cbranch_scc1 .LBB0_891
	s_and_saveexec_b64 s[72:73], s[70:71]
	s_cbranch_execz .LBB0_886
	s_branch .LBB0_894

; __device__ __forceinline__ unsigned xb_ld(unsigned* p)              { return __hip_atomic_load(p, __ATOMIC_RELAXED, __HIP_MEMORY_SCOPE_AGENT); }
; __device__ __forceinline__ void xcd_barrier_complete(unsigned* bar, unsigned x, unsigned& nloc, unsigned& nx) {
;     ...
;     for (;;) {
;         sum = 0u; cnt = 0u; mine = 0u;
; #pragma unroll
;         for (unsigned j = 0; j < 16; ++j) { const unsigned c = xb_ld(&bar[XB_XCNT(j)]); sum += c; cnt += (c > 0u) ? 1u : 0u; mine = (j == x) ? c : mine; }
;         if (sum == G) break;
;         __builtin_amdgcn_s_sleep(1);
;         if ((++sp & 255u) == 0u) { if (xb_ld(&bar[XB_TMO])) break; if (sp > XB_SPIN_CAP) { atomicAdd(&bar[XB_TMO], 1u); break; } }
;     }
.LBB0_1400:
	v_mov_b32_e32 v18, 0
	s_waitcnt lgkmcnt(0)
	global_load_dword v0, v18, s[4:5] sc1
	global_load_dword v2, v18, s[6:7] sc1
	global_load_dword v3, v18, s[8:9] sc1
	global_load_dword v4, v18, s[10:11] sc1
	global_load_dword v5, v18, s[12:13] sc1
	global_load_dword v6, v18, s[14:15] sc1
	global_load_dword v7, v18, s[16:17] sc1
	global_load_dword v8, v18, s[18:19] sc1
	global_load_dword v9, v18, s[20:21] sc1
	global_load_dword v10, v18, s[22:23] sc1
	global_load_dword v11, v18, s[24:25] sc1
	global_load_dword v12, v18, s[26:27] sc1
	global_load_dword v13, v18, s[28:29] sc1
	global_load_dword v14, v18, s[30:31] sc1
	global_load_dword v15, v18, s[36:37] sc1
	global_load_dword v16, v18, s[38:39] sc1
	v_readlane_b32 s48, v254, 8
	s_or_b64 s[46:47], s[46:47], exec
	s_or_b64 s[44:45], s[44:45], exec
	s_waitcnt vmcnt(0) lgkmcnt(0)
	v_add_u32_e32 v6, v2, v0
	v_add_u32_e32 v6, v6, v3
	v_add_u32_e32 v8, v6, v4
	v_add_u32_e32 v8, v8, v5
	v_add_u32_e32 v10, v8, v6
	v_add_u32_e32 v10, v10, v7
	v_add_u32_e32 v12, v10, v8
	v_add_u32_e32 v12, v12, v9
	v_add_u32_e32 v14, v12, v10
	v_add_u32_e32 v14, v14, v11
	v_add_u32_e32 v16, v14, v12
	v_add_u32_e32 v16, v16, v13
	v_add_u32_e32 v18, v16, v14
	v_add_u32_e32 v18, v18, v15
	v_add_u32_e32 v17, v18, v16
	v_cmp_ne_u32_e32 vcc, s48, v17
	s_and_saveexec_b64 s[48:49], vcc
	s_cbranch_execz .LBB0_1399
	s_and_b32 s52, s60, 0xff
	s_mov_b64 s[50:51], -1
	s_cmp_eq_u32 s52, 0
	s_mov_b64 s[68:69], -1
	s_mov_b64 s[52:53], -1
	s_sleep 1
	s_cbranch_scc1 .LBB0_1403
	s_and_saveexec_b64 s[70:71], s[68:69]
	s_cbranch_execz .LBB0_1398
	s_branch .LBB0_1406
